# out-projection epilogue hand-written: residual loads prefetched 3 row groups ahead, counted vmcnt
# baseline (speedup 1.0000x reference)
; __device__ __forceinline__ unsigned cvt_pk_bf16(float lo, float hi) { unsigned r; asm volatile("v_cvt_pk_bf16_f32 %0, %1, %2" : "=v"(r) : "v"(lo), "v"(hi)); return r; }
;     __device__ __forceinline__ void operator()(const f32x4 (&acc)[2][2][4][2], const Unit& u, int wr, int wc, int fr, int fq) const {
;         const int row0 = u.pm * BM + wr * 64 + fr, col0 = u.pn * BM + wc * 32 + 8 * fq;
; #pragma unroll
;         for (int ai = 0; ai < 2; ++ai)
; #pragma unroll
;             for (int m = 0; m < 4; ++m) { const int row = row0 + ai * HALF + m * 16; const size_t off = (size_t)row * ldc + col0; float s1 = 0.f, s2 = 0.f;
; #pragma unroll
;                 for (int bj = 0; bj < 2; ++bj) { const size_t o2 = off + bj * HALF; const f32x4 x0 = *(const f32x4*)(X + o2), x1 = *(const f32x4*)(X + o2 + 4);
;                     const f32x4 z0 = x0 * alpha + acc[ai][bj][m][0], z1 = x1 * alpha + acc[ai][bj][m][1];
;                     u32x4 w; w.x = cvt_pk_bf16(z0[0], z0[1]); w.y = cvt_pk_bf16(z0[2], z0[3]); w.z = cvt_pk_bf16(z1[0], z1[1]); w.w = cvt_pk_bf16(z1[2], z1[3]); *(u32x4*)(ZB + o2) = w;
;                     s1 += ((z0[0] + z0[1]) + (z0[2] + z0[3])) + ((z1[0] + z1[1]) + (z1[2] + z1[3]));
;                     s2 += ((z0[0] * z0[0] + z0[1] * z0[1]) + (z0[2] * z0[2] + z0[3] * z0[3])) + ((z1[0] * z1[0] + z1[1] * z1[1]) + (z1[2] * z1[2] + z1[3] * z1[3])); }
;                 s1 = sum_fq(s1); s2 = sum_fq(s2);
;                 if (fq == 0) { atomicAdd(ST + 2 * row, s1); atomicAdd(ST + 2 * row + 1, s2); } }
.LBB0_1136:
	v_lshl_add_u32 v138, s60, 8, v142
	v_lshl_or_b32 v139, s59, 8, v144
	v_lshl_add_u32 v140, v138, 11, v139
	v_lshlrev_b32_e32 v141, 2, v140
	v_lshlrev_b32_e32 v166, 1, v140
	v_lshlrev_b32_e32 v167, 3, v138
	global_load_dwordx4 v[174:177], v141, s[4:5]
	global_load_dwordx4 v[178:181], v141, s[4:5] offset:16
	global_load_dwordx4 v[182:185], v141, s[4:5] offset:512
	global_load_dwordx4 v[186:189], v141, s[4:5] offset:528
	v_add_u32_e32 v141, 0x20000, v141
	global_load_dwordx4 v[190:193], v141, s[4:5]
	global_load_dwordx4 v[194:197], v141, s[4:5] offset:16
	global_load_dwordx4 v[198:201], v141, s[4:5] offset:512
	global_load_dwordx4 v[202:205], v141, s[4:5] offset:528
	v_add_u32_e32 v141, 0x20000, v141
	global_load_dwordx4 v[206:209], v141, s[4:5]
	global_load_dwordx4 v[210:213], v141, s[4:5] offset:16
	global_load_dwordx4 v[224:227], v141, s[4:5] offset:512
	global_load_dwordx4 v[228:231], v141, s[4:5] offset:528
	v_add_u32_e32 v141, 0x20000, v141
	global_load_dwordx4 v[150:153], v141, s[4:5]
	global_load_dwordx4 v[154:157], v141, s[4:5] offset:16
	global_load_dwordx4 v[158:161], v141, s[4:5] offset:512
	global_load_dwordx4 v[162:165], v141, s[4:5] offset:528
	v_add_u32_e32 v141, 0xa0000, v141
	s_waitcnt vmcnt(12)
	v_pk_fma_f32 v[124:125], v[174:175], s[12:13], v[124:125] op_sel_hi:[1,0,1]
	v_pk_fma_f32 v[126:127], v[176:177], s[12:13], v[126:127] op_sel_hi:[1,0,1]
	v_pk_fma_f32 v[120:121], v[178:179], s[12:13], v[120:121] op_sel_hi:[1,0,1]
	v_pk_fma_f32 v[122:123], v[180:181], s[12:13], v[122:123] op_sel_hi:[1,0,1]
	v_pk_fma_f32 v[116:117], v[182:183], s[12:13], v[116:117] op_sel_hi:[1,0,1]
	v_pk_fma_f32 v[118:119], v[184:185], s[12:13], v[118:119] op_sel_hi:[1,0,1]
	v_pk_fma_f32 v[112:113], v[186:187], s[12:13], v[112:113] op_sel_hi:[1,0,1]
	v_pk_fma_f32 v[114:115], v[188:189], s[12:13], v[114:115] op_sel_hi:[1,0,1]
	v_cvt_pk_bf16_f32 v174, v124, v125
	v_cvt_pk_bf16_f32 v175, v126, v127
	v_cvt_pk_bf16_f32 v176, v120, v121
	v_cvt_pk_bf16_f32 v177, v122, v123
	global_store_dwordx4 v166, v[174:177], s[8:9]
	v_add_f32_e32 v184, v124, v125
	v_add_f32_e32 v185, v126, v127
	v_add_f32_e32 v184, v184, v185
	v_add_f32_e32 v185, v120, v121
	v_add_f32_e32 v186, v122, v123
	v_add_f32_e32 v185, v185, v186
	v_add_f32_e32 v184, v184, v185
	v_add_f32_e32 v182, 0, v184
	v_mul_f32_e32 v184, v125, v125
	v_mul_f32_e32 v185, v127, v127
	v_fmac_f32_e32 v184, v124, v124
	v_fmac_f32_e32 v185, v126, v126
	v_add_f32_e32 v184, v184, v185
	v_mul_f32_e32 v185, v121, v121
	v_mul_f32_e32 v186, v123, v123
	v_fmac_f32_e32 v185, v120, v120
	v_fmac_f32_e32 v186, v122, v122
	v_add_f32_e32 v185, v185, v186
	v_add_f32_e32 v183, v184, v185
	v_cvt_pk_bf16_f32 v178, v116, v117
	v_cvt_pk_bf16_f32 v179, v118, v119
	v_cvt_pk_bf16_f32 v180, v112, v113
	v_cvt_pk_bf16_f32 v181, v114, v115
	global_store_dwordx4 v166, v[178:181], s[8:9] offset:256
	v_add_f32_e32 v184, v116, v117
	v_add_f32_e32 v185, v118, v119
	v_add_f32_e32 v184, v184, v185
	v_add_f32_e32 v185, v112, v113
	v_add_f32_e32 v186, v114, v115
	v_add_f32_e32 v185, v185, v186
	v_add_f32_e32 v184, v184, v185
	v_add_f32_e32 v182, v182, v184
	v_mul_f32_e32 v184, v117, v117
	v_mul_f32_e32 v185, v119, v119
	v_fmac_f32_e32 v184, v116, v116
	v_fmac_f32_e32 v185, v118, v118
	v_add_f32_e32 v184, v184, v185
	v_mul_f32_e32 v185, v113, v113
	v_mul_f32_e32 v186, v115, v115
	v_fmac_f32_e32 v185, v112, v112
	v_fmac_f32_e32 v186, v114, v114
	v_add_f32_e32 v185, v185, v186
	v_add_f32_e32 v184, v184, v185
	v_add_f32_e32 v183, v183, v184
	v_mov_b32_e32 v184, v182
	v_mov_b32_e32 v185, v183
	s_nop 1
	v_permlane16_swap_b32_e32 v182, v184
	v_permlane16_swap_b32_e32 v183, v185
	v_add_f32_e32 v182, v182, v184
	v_add_f32_e32 v183, v183, v185
	v_mov_b32_e32 v184, v182
	v_mov_b32_e32 v185, v183
	s_nop 1
	v_permlane32_swap_b32_e32 v182, v184
	v_permlane32_swap_b32_e32 v183, v185
	v_add_f32_e32 v182, v182, v184
	v_add_f32_e32 v183, v183, v185
	s_and_saveexec_b64 s[0:1], s[40:41]
	global_atomic_add_f32 v167, v182, s[44:45]
	global_atomic_add_f32 v167, v183, s[44:45] offset:4
	s_or_b64 exec, exec, s[0:1]
	v_add_u32_e32 v166, 0x10000, v166
	global_load_dwordx4 v[174:177], v141, s[4:5]
	global_load_dwordx4 v[178:181], v141, s[4:5] offset:16
	global_load_dwordx4 v[182:185], v141, s[4:5] offset:512
	global_load_dwordx4 v[186:189], v141, s[4:5] offset:528
	v_add_u32_e32 v141, 0x20000, v141
	s_waitcnt vmcnt(16)
; __device__ __forceinline__ unsigned cvt_pk_bf16(float lo, float hi) { unsigned r; asm volatile("v_cvt_pk_bf16_f32 %0, %1, %2" : "=v"(r) : "v"(lo), "v"(hi)); return r; }
;     __device__ __forceinline__ void operator()(const f32x4 (&acc)[2][2][4][2], const Unit& u, int wr, int wc, int fr, int fq) const {
;         const int row0 = u.pm * BM + wr * 64 + fr, col0 = u.pn * BM + wc * 32 + 8 * fq;
; #pragma unroll
;         for (int ai = 0; ai < 2; ++ai)
; #pragma unroll
;             for (int m = 0; m < 4; ++m) { const int row = row0 + ai * HALF + m * 16; const size_t off = (size_t)row * ldc + col0; float s1 = 0.f, s2 = 0.f;
; #pragma unroll
;                 for (int bj = 0; bj < 2; ++bj) { const size_t o2 = off + bj * HALF; const f32x4 x0 = *(const f32x4*)(X + o2), x1 = *(const f32x4*)(X + o2 + 4);
;                     const f32x4 z0 = x0 * alpha + acc[ai][bj][m][0], z1 = x1 * alpha + acc[ai][bj][m][1];
;                     u32x4 w; w.x = cvt_pk_bf16(z0[0], z0[1]); w.y = cvt_pk_bf16(z0[2], z0[3]); w.z = cvt_pk_bf16(z1[0], z1[1]); w.w = cvt_pk_bf16(z1[2], z1[3]); *(u32x4*)(ZB + o2) = w;
;                     s1 += ((z0[0] + z0[1]) + (z0[2] + z0[3])) + ((z1[0] + z1[1]) + (z1[2] + z1[3]));
;                     s2 += ((z0[0] * z0[0] + z0[1] * z0[1]) + (z0[2] * z0[2] + z0[3] * z0[3])) + ((z1[0] * z1[0] + z1[1] * z1[1]) + (z1[2] * z1[2] + z1[3] * z1[3])); }
;                 s1 = sum_fq(s1); s2 = sum_fq(s2);
;                 if (fq == 0) { atomicAdd(ST + 2 * row, s1); atomicAdd(ST + 2 * row + 1, s2); } }
	v_pk_fma_f32 v[108:109], v[190:191], s[12:13], v[108:109] op_sel_hi:[1,0,1]
	v_pk_fma_f32 v[110:111], v[192:193], s[12:13], v[110:111] op_sel_hi:[1,0,1]
	v_pk_fma_f32 v[104:105], v[194:195], s[12:13], v[104:105] op_sel_hi:[1,0,1]
	v_pk_fma_f32 v[106:107], v[196:197], s[12:13], v[106:107] op_sel_hi:[1,0,1]
	v_pk_fma_f32 v[100:101], v[198:199], s[12:13], v[100:101] op_sel_hi:[1,0,1]
	v_pk_fma_f32 v[102:103], v[200:201], s[12:13], v[102:103] op_sel_hi:[1,0,1]
	v_pk_fma_f32 v[96:97], v[202:203], s[12:13], v[96:97] op_sel_hi:[1,0,1]
	v_pk_fma_f32 v[98:99], v[204:205], s[12:13], v[98:99] op_sel_hi:[1,0,1]
	v_cvt_pk_bf16_f32 v190, v108, v109
	v_cvt_pk_bf16_f32 v191, v110, v111
	v_cvt_pk_bf16_f32 v192, v104, v105
	v_cvt_pk_bf16_f32 v193, v106, v107
	global_store_dwordx4 v166, v[190:193], s[8:9]
	v_add_f32_e32 v200, v108, v109
	v_add_f32_e32 v201, v110, v111
	v_add_f32_e32 v200, v200, v201
	v_add_f32_e32 v201, v104, v105
	v_add_f32_e32 v202, v106, v107
	v_add_f32_e32 v201, v201, v202
	v_add_f32_e32 v200, v200, v201
	v_add_f32_e32 v198, 0, v200
	v_mul_f32_e32 v200, v109, v109
	v_mul_f32_e32 v201, v111, v111
	v_fmac_f32_e32 v200, v108, v108
	v_fmac_f32_e32 v201, v110, v110
	v_add_f32_e32 v200, v200, v201
	v_mul_f32_e32 v201, v105, v105
	v_mul_f32_e32 v202, v107, v107
	v_fmac_f32_e32 v201, v104, v104
	v_fmac_f32_e32 v202, v106, v106
	v_add_f32_e32 v201, v201, v202
	v_add_f32_e32 v199, v200, v201
	v_cvt_pk_bf16_f32 v194, v100, v101
	v_cvt_pk_bf16_f32 v195, v102, v103
	v_cvt_pk_bf16_f32 v196, v96, v97
	v_cvt_pk_bf16_f32 v197, v98, v99
	global_store_dwordx4 v166, v[194:197], s[8:9] offset:256
	v_add_f32_e32 v200, v100, v101
	v_add_f32_e32 v201, v102, v103
	v_add_f32_e32 v200, v200, v201
	v_add_f32_e32 v201, v96, v97
	v_add_f32_e32 v202, v98, v99
	v_add_f32_e32 v201, v201, v202
	v_add_f32_e32 v200, v200, v201
	v_add_f32_e32 v198, v198, v200
	v_mul_f32_e32 v200, v101, v101
	v_mul_f32_e32 v201, v103, v103
	v_fmac_f32_e32 v200, v100, v100
	v_fmac_f32_e32 v201, v102, v102
	v_add_f32_e32 v200, v200, v201
	v_mul_f32_e32 v201, v97, v97
	v_mul_f32_e32 v202, v99, v99
	v_fmac_f32_e32 v201, v96, v96
	v_fmac_f32_e32 v202, v98, v98
	v_add_f32_e32 v201, v201, v202
	v_add_f32_e32 v200, v200, v201
	v_add_f32_e32 v199, v199, v200
	v_mov_b32_e32 v200, v198
	v_mov_b32_e32 v201, v199
	s_nop 1
	v_permlane16_swap_b32_e32 v198, v200
	v_permlane16_swap_b32_e32 v199, v201
	v_add_f32_e32 v198, v198, v200
	v_add_f32_e32 v199, v199, v201
	v_mov_b32_e32 v200, v198
	v_mov_b32_e32 v201, v199
	s_nop 1
	v_permlane32_swap_b32_e32 v198, v200
	v_permlane32_swap_b32_e32 v199, v201
	v_add_f32_e32 v198, v198, v200
	v_add_f32_e32 v199, v199, v201
	s_and_saveexec_b64 s[0:1], s[40:41]
	global_atomic_add_f32 v167, v198, s[44:45] offset:128
	global_atomic_add_f32 v167, v199, s[44:45] offset:132
	s_or_b64 exec, exec, s[0:1]
	v_add_u32_e32 v166, 0x10000, v166
	global_load_dwordx4 v[190:193], v141, s[4:5]
	global_load_dwordx4 v[194:197], v141, s[4:5] offset:16
	global_load_dwordx4 v[198:201], v141, s[4:5] offset:512
	global_load_dwordx4 v[202:205], v141, s[4:5] offset:528
	v_add_u32_e32 v141, 0x20000, v141
	s_waitcnt vmcnt(20)
	v_pk_fma_f32 v[92:93], v[206:207], s[12:13], v[92:93] op_sel_hi:[1,0,1]
	v_pk_fma_f32 v[94:95], v[208:209], s[12:13], v[94:95] op_sel_hi:[1,0,1]
	v_pk_fma_f32 v[88:89], v[210:211], s[12:13], v[88:89] op_sel_hi:[1,0,1]
	v_pk_fma_f32 v[90:91], v[212:213], s[12:13], v[90:91] op_sel_hi:[1,0,1]
	v_pk_fma_f32 v[84:85], v[224:225], s[12:13], v[84:85] op_sel_hi:[1,0,1]
	v_pk_fma_f32 v[86:87], v[226:227], s[12:13], v[86:87] op_sel_hi:[1,0,1]
	v_pk_fma_f32 v[80:81], v[228:229], s[12:13], v[80:81] op_sel_hi:[1,0,1]
	v_pk_fma_f32 v[82:83], v[230:231], s[12:13], v[82:83] op_sel_hi:[1,0,1]
	v_cvt_pk_bf16_f32 v206, v92, v93
	v_cvt_pk_bf16_f32 v207, v94, v95
	v_cvt_pk_bf16_f32 v208, v88, v89
	v_cvt_pk_bf16_f32 v209, v90, v91
	global_store_dwordx4 v166, v[206:209], s[8:9]
	v_add_f32_e32 v226, v92, v93
	v_add_f32_e32 v227, v94, v95
	v_add_f32_e32 v226, v226, v227
	v_add_f32_e32 v227, v88, v89
	v_add_f32_e32 v228, v90, v91
	v_add_f32_e32 v227, v227, v228
	v_add_f32_e32 v226, v226, v227
	v_add_f32_e32 v224, 0, v226
	v_mul_f32_e32 v226, v93, v93
	v_mul_f32_e32 v227, v95, v95
	v_fmac_f32_e32 v226, v92, v92
	v_fmac_f32_e32 v227, v94, v94
	v_add_f32_e32 v226, v226, v227
	v_mul_f32_e32 v227, v89, v89
	v_mul_f32_e32 v228, v91, v91
	v_fmac_f32_e32 v227, v88, v88
	v_fmac_f32_e32 v228, v90, v90
	v_add_f32_e32 v227, v227, v228
	v_add_f32_e32 v225, v226, v227
	v_cvt_pk_bf16_f32 v210, v84, v85
	v_cvt_pk_bf16_f32 v211, v86, v87
	v_cvt_pk_bf16_f32 v212, v80, v81
	v_cvt_pk_bf16_f32 v213, v82, v83
	global_store_dwordx4 v166, v[210:213], s[8:9] offset:256
	v_add_f32_e32 v226, v84, v85
	v_add_f32_e32 v227, v86, v87
	v_add_f32_e32 v226, v226, v227
	v_add_f32_e32 v227, v80, v81
	v_add_f32_e32 v228, v82, v83
	v_add_f32_e32 v227, v227, v228
	v_add_f32_e32 v226, v226, v227
	v_add_f32_e32 v224, v224, v226
	v_mul_f32_e32 v226, v85, v85
	v_mul_f32_e32 v227, v87, v87
	v_fmac_f32_e32 v226, v84, v84
	v_fmac_f32_e32 v227, v86, v86
	v_add_f32_e32 v226, v226, v227
	v_mul_f32_e32 v227, v81, v81
	v_mul_f32_e32 v228, v83, v83
	v_fmac_f32_e32 v227, v80, v80
	v_fmac_f32_e32 v228, v82, v82
	v_add_f32_e32 v227, v227, v228
	v_add_f32_e32 v226, v226, v227
	v_add_f32_e32 v225, v225, v226
	v_mov_b32_e32 v226, v224
	v_mov_b32_e32 v227, v225
	s_nop 1
	v_permlane16_swap_b32_e32 v224, v226
	v_permlane16_swap_b32_e32 v225, v227
	v_add_f32_e32 v224, v224, v226
	v_add_f32_e32 v225, v225, v227
	v_mov_b32_e32 v226, v224
	v_mov_b32_e32 v227, v225
	s_nop 1
	v_permlane32_swap_b32_e32 v224, v226
	v_permlane32_swap_b32_e32 v225, v227
	v_add_f32_e32 v224, v224, v226
	v_add_f32_e32 v225, v225, v227
	s_and_saveexec_b64 s[0:1], s[40:41]
	global_atomic_add_f32 v167, v224, s[44:45] offset:256
	global_atomic_add_f32 v167, v225, s[44:45] offset:260
	s_or_b64 exec, exec, s[0:1]
	v_add_u32_e32 v166, 0x10000, v166
	global_load_dwordx4 v[206:209], v141, s[4:5]
	global_load_dwordx4 v[210:213], v141, s[4:5] offset:16
	global_load_dwordx4 v[224:227], v141, s[4:5] offset:512
	global_load_dwordx4 v[228:231], v141, s[4:5] offset:528
	v_add_u32_e32 v141, 0x20000, v141
	s_waitcnt vmcnt(24)
; __device__ __forceinline__ unsigned cvt_pk_bf16(float lo, float hi) { unsigned r; asm volatile("v_cvt_pk_bf16_f32 %0, %1, %2" : "=v"(r) : "v"(lo), "v"(hi)); return r; }
;     __device__ __forceinline__ void operator()(const f32x4 (&acc)[2][2][4][2], const Unit& u, int wr, int wc, int fr, int fq) const {
;         const int row0 = u.pm * BM + wr * 64 + fr, col0 = u.pn * BM + wc * 32 + 8 * fq;
; #pragma unroll
;         for (int ai = 0; ai < 2; ++ai)
; #pragma unroll
;             for (int m = 0; m < 4; ++m) { const int row = row0 + ai * HALF + m * 16; const size_t off = (size_t)row * ldc + col0; float s1 = 0.f, s2 = 0.f;
; #pragma unroll
;                 for (int bj = 0; bj < 2; ++bj) { const size_t o2 = off + bj * HALF; const f32x4 x0 = *(const f32x4*)(X + o2), x1 = *(const f32x4*)(X + o2 + 4);
;                     const f32x4 z0 = x0 * alpha + acc[ai][bj][m][0], z1 = x1 * alpha + acc[ai][bj][m][1];
;                     u32x4 w; w.x = cvt_pk_bf16(z0[0], z0[1]); w.y = cvt_pk_bf16(z0[2], z0[3]); w.z = cvt_pk_bf16(z1[0], z1[1]); w.w = cvt_pk_bf16(z1[2], z1[3]); *(u32x4*)(ZB + o2) = w;
;                     s1 += ((z0[0] + z0[1]) + (z0[2] + z0[3])) + ((z1[0] + z1[1]) + (z1[2] + z1[3]));
;                     s2 += ((z0[0] * z0[0] + z0[1] * z0[1]) + (z0[2] * z0[2] + z0[3] * z0[3])) + ((z1[0] * z1[0] + z1[1] * z1[1]) + (z1[2] * z1[2] + z1[3] * z1[3])); }
;                 s1 = sum_fq(s1); s2 = sum_fq(s2);
;                 if (fq == 0) { atomicAdd(ST + 2 * row, s1); atomicAdd(ST + 2 * row + 1, s2); } }
	v_pk_fma_f32 v[76:77], v[150:151], s[12:13], v[76:77] op_sel_hi:[1,0,1]
	v_pk_fma_f32 v[78:79], v[152:153], s[12:13], v[78:79] op_sel_hi:[1,0,1]
	v_pk_fma_f32 v[72:73], v[154:155], s[12:13], v[72:73] op_sel_hi:[1,0,1]
	v_pk_fma_f32 v[74:75], v[156:157], s[12:13], v[74:75] op_sel_hi:[1,0,1]
	v_pk_fma_f32 v[68:69], v[158:159], s[12:13], v[68:69] op_sel_hi:[1,0,1]
	v_pk_fma_f32 v[70:71], v[160:161], s[12:13], v[70:71] op_sel_hi:[1,0,1]
	v_pk_fma_f32 v[64:65], v[162:163], s[12:13], v[64:65] op_sel_hi:[1,0,1]
	v_pk_fma_f32 v[66:67], v[164:165], s[12:13], v[66:67] op_sel_hi:[1,0,1]
	v_cvt_pk_bf16_f32 v150, v76, v77
	v_cvt_pk_bf16_f32 v151, v78, v79
	v_cvt_pk_bf16_f32 v152, v72, v73
	v_cvt_pk_bf16_f32 v153, v74, v75
	global_store_dwordx4 v166, v[150:153], s[8:9]
	v_add_f32_e32 v160, v76, v77
	v_add_f32_e32 v161, v78, v79
	v_add_f32_e32 v160, v160, v161
	v_add_f32_e32 v161, v72, v73
	v_add_f32_e32 v162, v74, v75
	v_add_f32_e32 v161, v161, v162
	v_add_f32_e32 v160, v160, v161
	v_add_f32_e32 v158, 0, v160
	v_mul_f32_e32 v160, v77, v77
	v_mul_f32_e32 v161, v79, v79
	v_fmac_f32_e32 v160, v76, v76
	v_fmac_f32_e32 v161, v78, v78
	v_add_f32_e32 v160, v160, v161
	v_mul_f32_e32 v161, v73, v73
	v_mul_f32_e32 v162, v75, v75
	v_fmac_f32_e32 v161, v72, v72
	v_fmac_f32_e32 v162, v74, v74
	v_add_f32_e32 v161, v161, v162
	v_add_f32_e32 v159, v160, v161
	v_cvt_pk_bf16_f32 v154, v68, v69
	v_cvt_pk_bf16_f32 v155, v70, v71
	v_cvt_pk_bf16_f32 v156, v64, v65
	v_cvt_pk_bf16_f32 v157, v66, v67
	global_store_dwordx4 v166, v[154:157], s[8:9] offset:256
	v_add_f32_e32 v160, v68, v69
	v_add_f32_e32 v161, v70, v71
	v_add_f32_e32 v160, v160, v161
	v_add_f32_e32 v161, v64, v65
	v_add_f32_e32 v162, v66, v67
	v_add_f32_e32 v161, v161, v162
	v_add_f32_e32 v160, v160, v161
	v_add_f32_e32 v158, v158, v160
	v_mul_f32_e32 v160, v69, v69
	v_mul_f32_e32 v161, v71, v71
	v_fmac_f32_e32 v160, v68, v68
	v_fmac_f32_e32 v161, v70, v70
	v_add_f32_e32 v160, v160, v161
	v_mul_f32_e32 v161, v65, v65
	v_mul_f32_e32 v162, v67, v67
	v_fmac_f32_e32 v161, v64, v64
	v_fmac_f32_e32 v162, v66, v66
	v_add_f32_e32 v161, v161, v162
	v_add_f32_e32 v160, v160, v161
	v_add_f32_e32 v159, v159, v160
	v_mov_b32_e32 v160, v158
	v_mov_b32_e32 v161, v159
	s_nop 1
	v_permlane16_swap_b32_e32 v158, v160
	v_permlane16_swap_b32_e32 v159, v161
	v_add_f32_e32 v158, v158, v160
	v_add_f32_e32 v159, v159, v161
	v_mov_b32_e32 v160, v158
	v_mov_b32_e32 v161, v159
	s_nop 1
	v_permlane32_swap_b32_e32 v158, v160
	v_permlane32_swap_b32_e32 v159, v161
	v_add_f32_e32 v158, v158, v160
	v_add_f32_e32 v159, v159, v161
	s_and_saveexec_b64 s[0:1], s[40:41]
	global_atomic_add_f32 v167, v158, s[44:45] offset:384
	global_atomic_add_f32 v167, v159, s[44:45] offset:388
	s_or_b64 exec, exec, s[0:1]
	v_add_u32_e32 v166, 0x50000, v166
	global_load_dwordx4 v[150:153], v141, s[4:5]
	global_load_dwordx4 v[154:157], v141, s[4:5] offset:16
	global_load_dwordx4 v[158:161], v141, s[4:5] offset:512
	global_load_dwordx4 v[162:165], v141, s[4:5] offset:528
	s_waitcnt vmcnt(24)
	v_pk_fma_f32 v[60:61], v[174:175], s[12:13], v[60:61] op_sel_hi:[1,0,1]
	v_pk_fma_f32 v[62:63], v[176:177], s[12:13], v[62:63] op_sel_hi:[1,0,1]
	v_pk_fma_f32 v[56:57], v[178:179], s[12:13], v[56:57] op_sel_hi:[1,0,1]
	v_pk_fma_f32 v[58:59], v[180:181], s[12:13], v[58:59] op_sel_hi:[1,0,1]
	v_pk_fma_f32 v[52:53], v[182:183], s[12:13], v[52:53] op_sel_hi:[1,0,1]
	v_pk_fma_f32 v[54:55], v[184:185], s[12:13], v[54:55] op_sel_hi:[1,0,1]
	v_pk_fma_f32 v[48:49], v[186:187], s[12:13], v[48:49] op_sel_hi:[1,0,1]
	v_pk_fma_f32 v[50:51], v[188:189], s[12:13], v[50:51] op_sel_hi:[1,0,1]
	v_cvt_pk_bf16_f32 v174, v60, v61
	v_cvt_pk_bf16_f32 v175, v62, v63
	v_cvt_pk_bf16_f32 v176, v56, v57
	v_cvt_pk_bf16_f32 v177, v58, v59
	global_store_dwordx4 v166, v[174:177], s[8:9]
	v_add_f32_e32 v184, v60, v61
	v_add_f32_e32 v185, v62, v63
	v_add_f32_e32 v184, v184, v185
	v_add_f32_e32 v185, v56, v57
	v_add_f32_e32 v186, v58, v59
	v_add_f32_e32 v185, v185, v186
	v_add_f32_e32 v184, v184, v185
	v_add_f32_e32 v182, 0, v184
	v_mul_f32_e32 v184, v61, v61
	v_mul_f32_e32 v185, v63, v63
	v_fmac_f32_e32 v184, v60, v60
	v_fmac_f32_e32 v185, v62, v62
	v_add_f32_e32 v184, v184, v185
	v_mul_f32_e32 v185, v57, v57
	v_mul_f32_e32 v186, v59, v59
	v_fmac_f32_e32 v185, v56, v56
	v_fmac_f32_e32 v186, v58, v58
	v_add_f32_e32 v185, v185, v186
	v_add_f32_e32 v183, v184, v185
	v_cvt_pk_bf16_f32 v178, v52, v53
	v_cvt_pk_bf16_f32 v179, v54, v55
	v_cvt_pk_bf16_f32 v180, v48, v49
	v_cvt_pk_bf16_f32 v181, v50, v51
	global_store_dwordx4 v166, v[178:181], s[8:9] offset:256
	v_add_f32_e32 v184, v52, v53
	v_add_f32_e32 v185, v54, v55
	v_add_f32_e32 v184, v184, v185
	v_add_f32_e32 v185, v48, v49
	v_add_f32_e32 v186, v50, v51
	v_add_f32_e32 v185, v185, v186
	v_add_f32_e32 v184, v184, v185
	v_add_f32_e32 v182, v182, v184
	v_mul_f32_e32 v184, v53, v53
	v_mul_f32_e32 v185, v55, v55
	v_fmac_f32_e32 v184, v52, v52
	v_fmac_f32_e32 v185, v54, v54
	v_add_f32_e32 v184, v184, v185
	v_mul_f32_e32 v185, v49, v49
	v_mul_f32_e32 v186, v51, v51
	v_fmac_f32_e32 v185, v48, v48
	v_fmac_f32_e32 v186, v50, v50
	v_add_f32_e32 v185, v185, v186
	v_add_f32_e32 v184, v184, v185
	v_add_f32_e32 v183, v183, v184
	v_mov_b32_e32 v184, v182
	v_mov_b32_e32 v185, v183
	s_nop 1
	v_permlane16_swap_b32_e32 v182, v184
	v_permlane16_swap_b32_e32 v183, v185
	v_add_f32_e32 v182, v182, v184
	v_add_f32_e32 v183, v183, v185
	v_mov_b32_e32 v184, v182
	v_mov_b32_e32 v185, v183
	s_nop 1
	v_permlane32_swap_b32_e32 v182, v184
	v_permlane32_swap_b32_e32 v183, v185
	v_add_f32_e32 v182, v182, v184
	v_add_f32_e32 v183, v183, v185
	s_and_saveexec_b64 s[0:1], s[40:41]
	global_atomic_add_f32 v167, v182, s[44:45] offset:1024
	global_atomic_add_f32 v167, v183, s[44:45] offset:1028
	s_or_b64 exec, exec, s[0:1]
	v_add_u32_e32 v166, 0x10000, v166
	s_waitcnt vmcnt(20)
; __device__ __forceinline__ unsigned cvt_pk_bf16(float lo, float hi) { unsigned r; asm volatile("v_cvt_pk_bf16_f32 %0, %1, %2" : "=v"(r) : "v"(lo), "v"(hi)); return r; }
;     __device__ __forceinline__ void operator()(const f32x4 (&acc)[2][2][4][2], const Unit& u, int wr, int wc, int fr, int fq) const {
;         const int row0 = u.pm * BM + wr * 64 + fr, col0 = u.pn * BM + wc * 32 + 8 * fq;
; #pragma unroll
;         for (int ai = 0; ai < 2; ++ai)
; #pragma unroll
;             for (int m = 0; m < 4; ++m) { const int row = row0 + ai * HALF + m * 16; const size_t off = (size_t)row * ldc + col0; float s1 = 0.f, s2 = 0.f;
; #pragma unroll
;                 for (int bj = 0; bj < 2; ++bj) { const size_t o2 = off + bj * HALF; const f32x4 x0 = *(const f32x4*)(X + o2), x1 = *(const f32x4*)(X + o2 + 4);
;                     const f32x4 z0 = x0 * alpha + acc[ai][bj][m][0], z1 = x1 * alpha + acc[ai][bj][m][1];
;                     u32x4 w; w.x = cvt_pk_bf16(z0[0], z0[1]); w.y = cvt_pk_bf16(z0[2], z0[3]); w.z = cvt_pk_bf16(z1[0], z1[1]); w.w = cvt_pk_bf16(z1[2], z1[3]); *(u32x4*)(ZB + o2) = w;
;                     s1 += ((z0[0] + z0[1]) + (z0[2] + z0[3])) + ((z1[0] + z1[1]) + (z1[2] + z1[3]));
;                     s2 += ((z0[0] * z0[0] + z0[1] * z0[1]) + (z0[2] * z0[2] + z0[3] * z0[3])) + ((z1[0] * z1[0] + z1[1] * z1[1]) + (z1[2] * z1[2] + z1[3] * z1[3])); }
;                 s1 = sum_fq(s1); s2 = sum_fq(s2);
;                 if (fq == 0) { atomicAdd(ST + 2 * row, s1); atomicAdd(ST + 2 * row + 1, s2); } }
	v_pk_fma_f32 v[44:45], v[190:191], s[12:13], v[44:45] op_sel_hi:[1,0,1]
	v_pk_fma_f32 v[46:47], v[192:193], s[12:13], v[46:47] op_sel_hi:[1,0,1]
	v_pk_fma_f32 v[40:41], v[194:195], s[12:13], v[40:41] op_sel_hi:[1,0,1]
	v_pk_fma_f32 v[42:43], v[196:197], s[12:13], v[42:43] op_sel_hi:[1,0,1]
	v_pk_fma_f32 v[36:37], v[198:199], s[12:13], v[36:37] op_sel_hi:[1,0,1]
	v_pk_fma_f32 v[38:39], v[200:201], s[12:13], v[38:39] op_sel_hi:[1,0,1]
	v_pk_fma_f32 v[32:33], v[202:203], s[12:13], v[32:33] op_sel_hi:[1,0,1]
	v_pk_fma_f32 v[34:35], v[204:205], s[12:13], v[34:35] op_sel_hi:[1,0,1]
	v_cvt_pk_bf16_f32 v190, v44, v45
	v_cvt_pk_bf16_f32 v191, v46, v47
	v_cvt_pk_bf16_f32 v192, v40, v41
	v_cvt_pk_bf16_f32 v193, v42, v43
	global_store_dwordx4 v166, v[190:193], s[8:9]
	v_add_f32_e32 v200, v44, v45
	v_add_f32_e32 v201, v46, v47
	v_add_f32_e32 v200, v200, v201
	v_add_f32_e32 v201, v40, v41
	v_add_f32_e32 v202, v42, v43
	v_add_f32_e32 v201, v201, v202
	v_add_f32_e32 v200, v200, v201
	v_add_f32_e32 v198, 0, v200
	v_mul_f32_e32 v200, v45, v45
	v_mul_f32_e32 v201, v47, v47
	v_fmac_f32_e32 v200, v44, v44
	v_fmac_f32_e32 v201, v46, v46
	v_add_f32_e32 v200, v200, v201
	v_mul_f32_e32 v201, v41, v41
	v_mul_f32_e32 v202, v43, v43
	v_fmac_f32_e32 v201, v40, v40
	v_fmac_f32_e32 v202, v42, v42
	v_add_f32_e32 v201, v201, v202
	v_add_f32_e32 v199, v200, v201
	v_cvt_pk_bf16_f32 v194, v36, v37
	v_cvt_pk_bf16_f32 v195, v38, v39
	v_cvt_pk_bf16_f32 v196, v32, v33
	v_cvt_pk_bf16_f32 v197, v34, v35
	global_store_dwordx4 v166, v[194:197], s[8:9] offset:256
	v_add_f32_e32 v200, v36, v37
	v_add_f32_e32 v201, v38, v39
	v_add_f32_e32 v200, v200, v201
	v_add_f32_e32 v201, v32, v33
	v_add_f32_e32 v202, v34, v35
	v_add_f32_e32 v201, v201, v202
	v_add_f32_e32 v200, v200, v201
	v_add_f32_e32 v198, v198, v200
	v_mul_f32_e32 v200, v37, v37
	v_mul_f32_e32 v201, v39, v39
	v_fmac_f32_e32 v200, v36, v36
	v_fmac_f32_e32 v201, v38, v38
	v_add_f32_e32 v200, v200, v201
	v_mul_f32_e32 v201, v33, v33
	v_mul_f32_e32 v202, v35, v35
	v_fmac_f32_e32 v201, v32, v32
	v_fmac_f32_e32 v202, v34, v34
	v_add_f32_e32 v201, v201, v202
	v_add_f32_e32 v200, v200, v201
	v_add_f32_e32 v199, v199, v200
	v_mov_b32_e32 v200, v198
	v_mov_b32_e32 v201, v199
	s_nop 1
	v_permlane16_swap_b32_e32 v198, v200
	v_permlane16_swap_b32_e32 v199, v201
	v_add_f32_e32 v198, v198, v200
	v_add_f32_e32 v199, v199, v201
	v_mov_b32_e32 v200, v198
	v_mov_b32_e32 v201, v199
	s_nop 1
	v_permlane32_swap_b32_e32 v198, v200
	v_permlane32_swap_b32_e32 v199, v201
	v_add_f32_e32 v198, v198, v200
	v_add_f32_e32 v199, v199, v201
	s_and_saveexec_b64 s[0:1], s[40:41]
	global_atomic_add_f32 v167, v198, s[44:45] offset:1152
	global_atomic_add_f32 v167, v199, s[44:45] offset:1156
	s_or_b64 exec, exec, s[0:1]
	v_add_u32_e32 v166, 0x10000, v166
	s_waitcnt vmcnt(16)
; __device__ __forceinline__ unsigned cvt_pk_bf16(float lo, float hi) { unsigned r; asm volatile("v_cvt_pk_bf16_f32 %0, %1, %2" : "=v"(r) : "v"(lo), "v"(hi)); return r; }
;     __device__ __forceinline__ void operator()(const f32x4 (&acc)[2][2][4][2], const Unit& u, int wr, int wc, int fr, int fq) const {
;         const int row0 = u.pm * BM + wr * 64 + fr, col0 = u.pn * BM + wc * 32 + 8 * fq;
; #pragma unroll
;         for (int ai = 0; ai < 2; ++ai)
; #pragma unroll
;             for (int m = 0; m < 4; ++m) { const int row = row0 + ai * HALF + m * 16; const size_t off = (size_t)row * ldc + col0; float s1 = 0.f, s2 = 0.f;
; #pragma unroll
;                 for (int bj = 0; bj < 2; ++bj) { const size_t o2 = off + bj * HALF; const f32x4 x0 = *(const f32x4*)(X + o2), x1 = *(const f32x4*)(X + o2 + 4);
;                     const f32x4 z0 = x0 * alpha + acc[ai][bj][m][0], z1 = x1 * alpha + acc[ai][bj][m][1];
;                     u32x4 w; w.x = cvt_pk_bf16(z0[0], z0[1]); w.y = cvt_pk_bf16(z0[2], z0[3]); w.z = cvt_pk_bf16(z1[0], z1[1]); w.w = cvt_pk_bf16(z1[2], z1[3]); *(u32x4*)(ZB + o2) = w;
;                     s1 += ((z0[0] + z0[1]) + (z0[2] + z0[3])) + ((z1[0] + z1[1]) + (z1[2] + z1[3]));
;                     s2 += ((z0[0] * z0[0] + z0[1] * z0[1]) + (z0[2] * z0[2] + z0[3] * z0[3])) + ((z1[0] * z1[0] + z1[1] * z1[1]) + (z1[2] * z1[2] + z1[3] * z1[3])); }
;                 s1 = sum_fq(s1); s2 = sum_fq(s2);
;                 if (fq == 0) { atomicAdd(ST + 2 * row, s1); atomicAdd(ST + 2 * row + 1, s2); } }
	v_pk_fma_f32 v[28:29], v[206:207], s[12:13], v[28:29] op_sel_hi:[1,0,1]
	v_pk_fma_f32 v[30:31], v[208:209], s[12:13], v[30:31] op_sel_hi:[1,0,1]
	v_pk_fma_f32 v[24:25], v[210:211], s[12:13], v[24:25] op_sel_hi:[1,0,1]
	v_pk_fma_f32 v[26:27], v[212:213], s[12:13], v[26:27] op_sel_hi:[1,0,1]
	v_pk_fma_f32 v[20:21], v[224:225], s[12:13], v[20:21] op_sel_hi:[1,0,1]
	v_pk_fma_f32 v[22:23], v[226:227], s[12:13], v[22:23] op_sel_hi:[1,0,1]
	v_pk_fma_f32 v[16:17], v[228:229], s[12:13], v[16:17] op_sel_hi:[1,0,1]
	v_pk_fma_f32 v[18:19], v[230:231], s[12:13], v[18:19] op_sel_hi:[1,0,1]
	v_cvt_pk_bf16_f32 v206, v28, v29
	v_cvt_pk_bf16_f32 v207, v30, v31
	v_cvt_pk_bf16_f32 v208, v24, v25
	v_cvt_pk_bf16_f32 v209, v26, v27
	global_store_dwordx4 v166, v[206:209], s[8:9]
	v_add_f32_e32 v226, v28, v29
	v_add_f32_e32 v227, v30, v31
	v_add_f32_e32 v226, v226, v227
	v_add_f32_e32 v227, v24, v25
	v_add_f32_e32 v228, v26, v27
	v_add_f32_e32 v227, v227, v228
	v_add_f32_e32 v226, v226, v227
	v_add_f32_e32 v224, 0, v226
	v_mul_f32_e32 v226, v29, v29
	v_mul_f32_e32 v227, v31, v31
	v_fmac_f32_e32 v226, v28, v28
	v_fmac_f32_e32 v227, v30, v30
	v_add_f32_e32 v226, v226, v227
	v_mul_f32_e32 v227, v25, v25
	v_mul_f32_e32 v228, v27, v27
	v_fmac_f32_e32 v227, v24, v24
	v_fmac_f32_e32 v228, v26, v26
	v_add_f32_e32 v227, v227, v228
	v_add_f32_e32 v225, v226, v227
	v_cvt_pk_bf16_f32 v210, v20, v21
	v_cvt_pk_bf16_f32 v211, v22, v23
	v_cvt_pk_bf16_f32 v212, v16, v17
	v_cvt_pk_bf16_f32 v213, v18, v19
	global_store_dwordx4 v166, v[210:213], s[8:9] offset:256
	v_add_f32_e32 v226, v20, v21
	v_add_f32_e32 v227, v22, v23
	v_add_f32_e32 v226, v226, v227
	v_add_f32_e32 v227, v16, v17
	v_add_f32_e32 v228, v18, v19
	v_add_f32_e32 v227, v227, v228
	v_add_f32_e32 v226, v226, v227
	v_add_f32_e32 v224, v224, v226
	v_mul_f32_e32 v226, v21, v21
	v_mul_f32_e32 v227, v23, v23
	v_fmac_f32_e32 v226, v20, v20
	v_fmac_f32_e32 v227, v22, v22
	v_add_f32_e32 v226, v226, v227
	v_mul_f32_e32 v227, v17, v17
	v_mul_f32_e32 v228, v19, v19
	v_fmac_f32_e32 v227, v16, v16
	v_fmac_f32_e32 v228, v18, v18
	v_add_f32_e32 v227, v227, v228
	v_add_f32_e32 v226, v226, v227
	v_add_f32_e32 v225, v225, v226
	v_mov_b32_e32 v226, v224
	v_mov_b32_e32 v227, v225
	s_nop 1
	v_permlane16_swap_b32_e32 v224, v226
	v_permlane16_swap_b32_e32 v225, v227
	v_add_f32_e32 v224, v224, v226
	v_add_f32_e32 v225, v225, v227
	v_mov_b32_e32 v226, v224
	v_mov_b32_e32 v227, v225
	s_nop 1
	v_permlane32_swap_b32_e32 v224, v226
	v_permlane32_swap_b32_e32 v225, v227
	v_add_f32_e32 v224, v224, v226
	v_add_f32_e32 v225, v225, v227
	s_and_saveexec_b64 s[0:1], s[40:41]
	global_atomic_add_f32 v167, v224, s[44:45] offset:1280
	global_atomic_add_f32 v167, v225, s[44:45] offset:1284
	s_or_b64 exec, exec, s[0:1]
	v_add_u32_e32 v166, 0x10000, v166
	s_waitcnt vmcnt(12)
	v_pk_fma_f32 v[12:13], v[150:151], s[12:13], v[12:13] op_sel_hi:[1,0,1]
	v_pk_fma_f32 v[14:15], v[152:153], s[12:13], v[14:15] op_sel_hi:[1,0,1]
	v_pk_fma_f32 v[8:9], v[154:155], s[12:13], v[8:9] op_sel_hi:[1,0,1]
	v_pk_fma_f32 v[10:11], v[156:157], s[12:13], v[10:11] op_sel_hi:[1,0,1]
	v_pk_fma_f32 v[4:5], v[158:159], s[12:13], v[4:5] op_sel_hi:[1,0,1]
	v_pk_fma_f32 v[6:7], v[160:161], s[12:13], v[6:7] op_sel_hi:[1,0,1]
	v_pk_fma_f32 v[0:1], v[162:163], s[12:13], v[0:1] op_sel_hi:[1,0,1]
	v_pk_fma_f32 v[2:3], v[164:165], s[12:13], v[2:3] op_sel_hi:[1,0,1]
	v_cvt_pk_bf16_f32 v150, v12, v13
	v_cvt_pk_bf16_f32 v151, v14, v15
	v_cvt_pk_bf16_f32 v152, v8, v9
	v_cvt_pk_bf16_f32 v153, v10, v11
	global_store_dwordx4 v166, v[150:153], s[8:9]
	v_add_f32_e32 v160, v12, v13
	v_add_f32_e32 v161, v14, v15
	v_add_f32_e32 v160, v160, v161
	v_add_f32_e32 v161, v8, v9
	v_add_f32_e32 v162, v10, v11
	v_add_f32_e32 v161, v161, v162
	v_add_f32_e32 v160, v160, v161
	v_add_f32_e32 v158, 0, v160
	v_mul_f32_e32 v160, v13, v13
	v_mul_f32_e32 v161, v15, v15
	v_fmac_f32_e32 v160, v12, v12
	v_fmac_f32_e32 v161, v14, v14
	v_add_f32_e32 v160, v160, v161
	v_mul_f32_e32 v161, v9, v9
	v_mul_f32_e32 v162, v11, v11
	v_fmac_f32_e32 v161, v8, v8
	v_fmac_f32_e32 v162, v10, v10
	v_add_f32_e32 v161, v161, v162
	v_add_f32_e32 v159, v160, v161
	v_cvt_pk_bf16_f32 v154, v4, v5
	v_cvt_pk_bf16_f32 v155, v6, v7
	v_cvt_pk_bf16_f32 v156, v0, v1
	v_cvt_pk_bf16_f32 v157, v2, v3
	global_store_dwordx4 v166, v[154:157], s[8:9] offset:256
	v_add_f32_e32 v160, v4, v5
	v_add_f32_e32 v161, v6, v7
	v_add_f32_e32 v160, v160, v161
	v_add_f32_e32 v161, v0, v1
	v_add_f32_e32 v162, v2, v3
	v_add_f32_e32 v161, v161, v162
	v_add_f32_e32 v160, v160, v161
	v_add_f32_e32 v158, v158, v160
	v_mul_f32_e32 v160, v5, v5
	v_mul_f32_e32 v161, v7, v7
	v_fmac_f32_e32 v160, v4, v4
	v_fmac_f32_e32 v161, v6, v6
	v_add_f32_e32 v160, v160, v161
	v_mul_f32_e32 v161, v1, v1
	v_mul_f32_e32 v162, v3, v3
	v_fmac_f32_e32 v161, v0, v0
	v_fmac_f32_e32 v162, v2, v2
	v_add_f32_e32 v161, v161, v162
	v_add_f32_e32 v160, v160, v161
	v_add_f32_e32 v159, v159, v160
	v_mov_b32_e32 v160, v158
	v_mov_b32_e32 v161, v159
	s_nop 1
	v_permlane16_swap_b32_e32 v158, v160
	v_permlane16_swap_b32_e32 v159, v161
	v_add_f32_e32 v158, v158, v160
	v_add_f32_e32 v159, v159, v161
	v_mov_b32_e32 v160, v158
	v_mov_b32_e32 v161, v159
	s_nop 1
	v_permlane32_swap_b32_e32 v158, v160
	v_permlane32_swap_b32_e32 v159, v161
	v_add_f32_e32 v158, v158, v160
	v_add_f32_e32 v159, v159, v161
	s_and_saveexec_b64 s[0:1], s[40:41]
	global_atomic_add_f32 v167, v158, s[44:45] offset:1408
	global_atomic_add_f32 v167, v159, s[44:45] offset:1412
	s_or_b64 exec, exec, s[0:1]
	s_mov_b64 s[0:1], exec
